# q-up rope epilogue: each stage's pending store issued (from register copies) after the stage's cos/sin loads, wait lowered to vmcnt(1) so it no longer covers the store
# speedup vs baseline: 1.0033x; 1.0033x over previous
.LBB0_510:
	v_mov_b64_e32 v[124:125], s[22:23]
	v_cvt_pk_bf16_f32 v163, v126, v127
	v_or_b32_e32 v126, 16, v146
	s_ashr_i32 s49, s48, 31
	v_mad_i64_i32 v[124:125], s[6:7], v146, s77, v[124:125]
	v_ashrrev_i32_e32 v127, 31, v126
	v_lshl_add_u64 v[124:125], s[48:49], 1, v[124:125]
	v_cvt_pk_bf16_f32 v164, v152, v153
	v_cvt_pk_bf16_f32 v165, v150, v151
	v_pk_mul_f32 v[150:151], v[114:115], s[38:39] op_sel_hi:[1,0]
	v_pk_mul_f32 v[152:153], v[112:113], s[38:39] op_sel_hi:[1,0]
	v_cndmask_b32_e64 v112, 0, 1, s[2:3]
	v_lshlrev_b64 v[114:115], 6, v[126:127]
	v_lshl_add_u64 v[124:125], v[124:125], 0, v[132:133]
	v_cvt_pk_bf16_f32 v162, v148, v149
	v_pk_mul_f32 v[118:119], v[118:119], s[38:39] op_sel_hi:[1,0]
	v_pk_mul_f32 v[148:149], v[116:117], s[38:39] op_sel_hi:[1,0]
	v_cmp_ne_u32_e64 s[6:7], 1, v112
	s_andn2_b64 vcc, exec, s[2:3]
	v_lshl_add_u64 v[112:113], v[138:139], 0, v[114:115]
	v_lshl_add_u64 v[114:115], v[140:141], 0, v[114:115]
	s_cbranch_vccz .Lqst_1
	global_store_dwordx4 v[124:125], v[162:165], off
	s_branch .LBB0_512
.Lqst_1:
	v_mov_b64_e32 v[192:193], v[124:125]
	v_mov_b64_e32 v[194:195], v[162:163]
	v_mov_b64_e32 v[196:197], v[164:165]
	global_load_dwordx4 v[162:165], v[114:115], off
	global_load_dwordx4 v[166:169], v[114:115], off offset:16
	global_load_dwordx4 v[170:173], v[112:113], off
	global_load_dwordx4 v[174:177], v[112:113], off offset:16
	global_store_dwordx4 v[192:193], v[194:197], off
	v_and_b32_e32 v117, 64, v160
	v_xor_b32_e32 v116, 32, v160
	v_add_u32_e32 v117, 64, v117
	v_cmp_lt_i32_e32 vcc, v116, v117
	s_nop 1
	v_cndmask_b32_e32 v116, v160, v116, vcc
	v_lshlrev_b32_e32 v127, 2, v116
	ds_bpermute_b32 v116, v127, v148
	ds_bpermute_b32 v178, v127, v152
	ds_bpermute_b32 v117, v127, v149
	ds_bpermute_b32 v180, v127, v118
	ds_bpermute_b32 v181, v127, v119
	ds_bpermute_b32 v182, v127, v150
	ds_bpermute_b32 v183, v127, v151
	ds_bpermute_b32 v179, v127, v153
	s_waitcnt vmcnt(1) lgkmcnt(0)
	v_pk_mul_f32 v[164:165], v[164:165], v[180:181]
	v_pk_mul_f32 v[116:117], v[162:163], v[116:117]
	v_pk_mul_f32 v[162:163], v[168:169], v[182:183]
	v_pk_mul_f32 v[166:167], v[166:167], v[178:179]
	v_pk_mul_f32 v[116:117], v[134:135], v[116:117]
	v_pk_mul_f32 v[164:165], v[136:137], v[164:165]
	v_pk_mul_f32 v[166:167], v[134:135], v[166:167]
	v_pk_mul_f32 v[162:163], v[136:137], v[162:163]
	v_pk_fma_f32 v[118:119], v[118:119], v[172:173], v[164:165]
	v_pk_fma_f32 v[148:149], v[148:149], v[170:171], v[116:117]
	v_pk_fma_f32 v[150:151], v[150:151], v[176:177], v[162:163]
	v_pk_fma_f32 v[152:153], v[152:153], v[174:175], v[166:167]
.LBB0_512:
	v_mov_b64_e32 v[116:117], s[22:23]
	v_cvt_pk_bf16_f32 v163, v118, v119
	v_or_b32_e32 v118, 32, v146
	v_mad_i64_i32 v[116:117], s[2:3], v126, s77, v[116:117]
	v_ashrrev_i32_e32 v119, 31, v118
	v_lshl_add_u64 v[116:117], s[48:49], 1, v[116:117]
	v_cvt_pk_bf16_f32 v162, v148, v149
	v_pk_mul_f32 v[148:149], v[106:107], s[38:39] op_sel_hi:[1,0]
	v_lshlrev_b64 v[106:107], 6, v[118:119]
	v_lshl_add_u64 v[116:117], v[116:117], 0, v[132:133]
	v_cvt_pk_bf16_f32 v164, v152, v153
	v_cvt_pk_bf16_f32 v165, v150, v151
	v_pk_mul_f32 v[110:111], v[110:111], s[38:39] op_sel_hi:[1,0]
	v_pk_mul_f32 v[126:127], v[108:109], s[38:39] op_sel_hi:[1,0]
	v_pk_mul_f32 v[150:151], v[104:105], s[38:39] op_sel_hi:[1,0]
	s_and_b64 vcc, exec, s[6:7]
	v_lshl_add_u64 v[104:105], v[138:139], 0, v[106:107]
	v_lshl_add_u64 v[106:107], v[140:141], 0, v[106:107]
	s_cbranch_vccz .Lqst_2
	global_store_dwordx4 v[116:117], v[162:165], off
	s_branch .LBB0_514
.Lqst_2:
	v_mov_b64_e32 v[192:193], v[116:117]
	v_mov_b64_e32 v[194:195], v[162:163]
	v_mov_b64_e32 v[196:197], v[164:165]
	global_load_dwordx4 v[162:165], v[106:107], off
	global_load_dwordx4 v[166:169], v[106:107], off offset:16
	global_load_dwordx4 v[170:173], v[104:105], off
	global_load_dwordx4 v[174:177], v[104:105], off offset:16
	global_store_dwordx4 v[192:193], v[194:197], off
	v_and_b32_e32 v109, 64, v160
	v_xor_b32_e32 v108, 32, v160
	v_add_u32_e32 v109, 64, v109
	v_cmp_lt_i32_e32 vcc, v108, v109
	s_nop 1
	v_cndmask_b32_e32 v108, v160, v108, vcc
	v_lshlrev_b32_e32 v119, 2, v108
	ds_bpermute_b32 v108, v119, v126
	ds_bpermute_b32 v152, v119, v150
	ds_bpermute_b32 v109, v119, v127
	ds_bpermute_b32 v178, v119, v110
	ds_bpermute_b32 v179, v119, v111
	ds_bpermute_b32 v180, v119, v148
	ds_bpermute_b32 v181, v119, v149
	ds_bpermute_b32 v153, v119, v151
	s_waitcnt vmcnt(1) lgkmcnt(0)
	v_pk_mul_f32 v[164:165], v[164:165], v[178:179]
	v_pk_mul_f32 v[108:109], v[162:163], v[108:109]
	v_pk_mul_f32 v[162:163], v[168:169], v[180:181]
	v_pk_mul_f32 v[152:153], v[166:167], v[152:153]
	v_pk_mul_f32 v[108:109], v[134:135], v[108:109]
	v_pk_mul_f32 v[164:165], v[136:137], v[164:165]
	v_pk_mul_f32 v[152:153], v[134:135], v[152:153]
	v_pk_mul_f32 v[162:163], v[136:137], v[162:163]
	v_pk_fma_f32 v[110:111], v[110:111], v[172:173], v[164:165]
	v_pk_fma_f32 v[126:127], v[126:127], v[170:171], v[108:109]
	v_pk_fma_f32 v[148:149], v[148:149], v[176:177], v[162:163]
	v_pk_fma_f32 v[150:151], v[150:151], v[174:175], v[152:153]
.LBB0_514:
	v_mov_b64_e32 v[108:109], s[22:23]
	v_cvt_pk_bf16_f32 v163, v110, v111
	v_or_b32_e32 v110, 48, v146
	v_mad_i64_i32 v[108:109], s[2:3], v118, s77, v[108:109]
	v_ashrrev_i32_e32 v111, 31, v110
	v_lshl_add_u64 v[108:109], s[48:49], 1, v[108:109]
	v_cvt_pk_bf16_f32 v162, v126, v127
	v_pk_mul_f32 v[126:127], v[98:99], s[38:39] op_sel_hi:[1,0]
	v_lshlrev_b64 v[98:99], 6, v[110:111]
	v_lshl_add_u64 v[108:109], v[108:109], 0, v[132:133]
	v_cvt_pk_bf16_f32 v164, v150, v151
	v_cvt_pk_bf16_f32 v165, v148, v149
	v_pk_mul_f32 v[102:103], v[102:103], s[38:39] op_sel_hi:[1,0]
	v_pk_mul_f32 v[118:119], v[100:101], s[38:39] op_sel_hi:[1,0]
	v_pk_mul_f32 v[148:149], v[96:97], s[38:39] op_sel_hi:[1,0]
	s_and_b64 vcc, exec, s[6:7]
	v_lshl_add_u64 v[96:97], v[138:139], 0, v[98:99]
	v_lshl_add_u64 v[98:99], v[140:141], 0, v[98:99]
	s_cbranch_vccz .Lqst_3
	global_store_dwordx4 v[108:109], v[162:165], off
	s_branch .LBB0_516
.Lqst_3:
	v_mov_b64_e32 v[192:193], v[108:109]
	v_mov_b64_e32 v[194:195], v[162:163]
	v_mov_b64_e32 v[196:197], v[164:165]
	global_load_dwordx4 v[150:153], v[98:99], off
	global_load_dwordx4 v[162:165], v[98:99], off offset:16
	global_load_dwordx4 v[166:169], v[96:97], off
	global_load_dwordx4 v[170:173], v[96:97], off offset:16
	global_store_dwordx4 v[192:193], v[194:197], off
	v_and_b32_e32 v101, 64, v160
	v_xor_b32_e32 v100, 32, v160
	v_add_u32_e32 v101, 64, v101
	v_cmp_lt_i32_e32 vcc, v100, v101
	s_nop 1
	v_cndmask_b32_e32 v100, v160, v100, vcc
	v_lshlrev_b32_e32 v111, 2, v100
	ds_bpermute_b32 v100, v111, v118
	ds_bpermute_b32 v174, v111, v148
	ds_bpermute_b32 v101, v111, v119
	ds_bpermute_b32 v176, v111, v102
	ds_bpermute_b32 v177, v111, v103
	ds_bpermute_b32 v178, v111, v126
	ds_bpermute_b32 v179, v111, v127
	ds_bpermute_b32 v175, v111, v149
	s_waitcnt vmcnt(1) lgkmcnt(0)
	v_pk_mul_f32 v[152:153], v[152:153], v[176:177]
	v_pk_mul_f32 v[100:101], v[150:151], v[100:101]
	v_pk_mul_f32 v[150:151], v[164:165], v[178:179]
	v_pk_mul_f32 v[162:163], v[162:163], v[174:175]
	v_pk_mul_f32 v[100:101], v[134:135], v[100:101]
	v_pk_mul_f32 v[152:153], v[136:137], v[152:153]
	v_pk_mul_f32 v[162:163], v[134:135], v[162:163]
	v_pk_mul_f32 v[150:151], v[136:137], v[150:151]
	v_pk_fma_f32 v[102:103], v[102:103], v[168:169], v[152:153]
	v_pk_fma_f32 v[118:119], v[118:119], v[166:167], v[100:101]
	v_pk_fma_f32 v[126:127], v[126:127], v[172:173], v[150:151]
	v_pk_fma_f32 v[148:149], v[148:149], v[170:171], v[162:163]
.LBB0_516:
	v_mov_b64_e32 v[100:101], s[22:23]
	v_cvt_pk_bf16_f32 v151, v102, v103
	v_add_u32_e32 v102, 0x80, v146
	v_mad_i64_i32 v[100:101], s[2:3], v110, s77, v[100:101]
	v_ashrrev_i32_e32 v103, 31, v102
	v_lshl_add_u64 v[100:101], s[48:49], 1, v[100:101]
	v_cvt_pk_bf16_f32 v150, v118, v119
	v_pk_mul_f32 v[118:119], v[90:91], s[38:39] op_sel_hi:[1,0]
	v_lshlrev_b64 v[90:91], 6, v[102:103]
	v_lshl_add_u64 v[100:101], v[100:101], 0, v[132:133]
	v_cvt_pk_bf16_f32 v152, v148, v149
	v_cvt_pk_bf16_f32 v153, v126, v127
	v_pk_mul_f32 v[94:95], v[94:95], s[38:39] op_sel_hi:[1,0]
	v_pk_mul_f32 v[110:111], v[92:93], s[38:39] op_sel_hi:[1,0]
	v_pk_mul_f32 v[126:127], v[88:89], s[38:39] op_sel_hi:[1,0]
	s_and_b64 vcc, exec, s[6:7]
	v_lshl_add_u64 v[88:89], v[138:139], 0, v[90:91]
	v_lshl_add_u64 v[90:91], v[140:141], 0, v[90:91]
	s_cbranch_vccz .Lqst_4
	global_store_dwordx4 v[100:101], v[150:153], off
	s_branch .LBB0_518
.Lqst_4:
	v_mov_b64_e32 v[192:193], v[100:101]
	v_mov_b64_e32 v[194:195], v[150:151]
	v_mov_b64_e32 v[196:197], v[152:153]
	global_load_dwordx4 v[148:151], v[90:91], off
	global_load_dwordx4 v[162:165], v[90:91], off offset:16
	global_load_dwordx4 v[166:169], v[88:89], off
	global_load_dwordx4 v[170:173], v[88:89], off offset:16
	global_store_dwordx4 v[192:193], v[194:197], off
	v_and_b32_e32 v93, 64, v160
	v_xor_b32_e32 v92, 32, v160
	v_add_u32_e32 v93, 64, v93
	v_cmp_lt_i32_e32 vcc, v92, v93
	s_nop 1
	v_cndmask_b32_e32 v92, v160, v92, vcc
	v_lshlrev_b32_e32 v103, 2, v92
	ds_bpermute_b32 v92, v103, v110
	ds_bpermute_b32 v152, v103, v126
	ds_bpermute_b32 v93, v103, v111
	ds_bpermute_b32 v174, v103, v94
	ds_bpermute_b32 v175, v103, v95
	ds_bpermute_b32 v176, v103, v118
	ds_bpermute_b32 v177, v103, v119
	ds_bpermute_b32 v153, v103, v127
	s_waitcnt vmcnt(1) lgkmcnt(0)
	v_pk_mul_f32 v[150:151], v[150:151], v[174:175]
	v_pk_mul_f32 v[92:93], v[148:149], v[92:93]
	v_pk_mul_f32 v[148:149], v[164:165], v[176:177]
	v_pk_mul_f32 v[152:153], v[162:163], v[152:153]
	v_pk_mul_f32 v[92:93], v[134:135], v[92:93]
	v_pk_mul_f32 v[150:151], v[136:137], v[150:151]
	v_pk_mul_f32 v[152:153], v[134:135], v[152:153]
	v_pk_mul_f32 v[148:149], v[136:137], v[148:149]
	v_pk_fma_f32 v[94:95], v[94:95], v[168:169], v[150:151]
	v_pk_fma_f32 v[110:111], v[110:111], v[166:167], v[92:93]
	v_pk_fma_f32 v[118:119], v[118:119], v[172:173], v[148:149]
	v_pk_fma_f32 v[126:127], v[126:127], v[170:171], v[152:153]
.LBB0_518:
	v_mov_b64_e32 v[92:93], s[22:23]
	v_cvt_pk_bf16_f32 v149, v94, v95
	v_add_u32_e32 v94, 0x90, v146
	v_mad_i64_i32 v[92:93], s[2:3], v102, s77, v[92:93]
	v_ashrrev_i32_e32 v95, 31, v94
	v_lshl_add_u64 v[92:93], s[48:49], 1, v[92:93]
	v_cvt_pk_bf16_f32 v148, v110, v111
	v_pk_mul_f32 v[110:111], v[82:83], s[38:39] op_sel_hi:[1,0]
	v_lshlrev_b64 v[82:83], 6, v[94:95]
	v_lshl_add_u64 v[92:93], v[92:93], 0, v[132:133]
	v_cvt_pk_bf16_f32 v150, v126, v127
	v_cvt_pk_bf16_f32 v151, v118, v119
	v_pk_mul_f32 v[86:87], v[86:87], s[38:39] op_sel_hi:[1,0]
	v_pk_mul_f32 v[102:103], v[84:85], s[38:39] op_sel_hi:[1,0]
	v_pk_mul_f32 v[118:119], v[80:81], s[38:39] op_sel_hi:[1,0]
	s_and_b64 vcc, exec, s[6:7]
	v_lshl_add_u64 v[80:81], v[138:139], 0, v[82:83]
	v_lshl_add_u64 v[82:83], v[140:141], 0, v[82:83]
	s_cbranch_vccz .Lqst_5
	global_store_dwordx4 v[92:93], v[148:151], off
	s_branch .LBB0_520
.Lqst_5:
	v_mov_b64_e32 v[192:193], v[92:93]
	v_mov_b64_e32 v[194:195], v[148:149]
	v_mov_b64_e32 v[196:197], v[150:151]
	global_load_dwordx4 v[148:151], v[82:83], off
	global_load_dwordx4 v[162:165], v[82:83], off offset:16
	global_load_dwordx4 v[166:169], v[80:81], off
	global_load_dwordx4 v[170:173], v[80:81], off offset:16
	global_store_dwordx4 v[192:193], v[194:197], off
	v_and_b32_e32 v85, 64, v160
	v_xor_b32_e32 v84, 32, v160
	v_add_u32_e32 v85, 64, v85
	v_cmp_lt_i32_e32 vcc, v84, v85
	s_nop 1
	v_cndmask_b32_e32 v84, v160, v84, vcc
	v_lshlrev_b32_e32 v95, 2, v84
	ds_bpermute_b32 v84, v95, v102
	ds_bpermute_b32 v126, v95, v118
	ds_bpermute_b32 v85, v95, v103
	ds_bpermute_b32 v152, v95, v86
	ds_bpermute_b32 v153, v95, v87
	ds_bpermute_b32 v174, v95, v110
	ds_bpermute_b32 v175, v95, v111
	ds_bpermute_b32 v127, v95, v119
	s_waitcnt vmcnt(1) lgkmcnt(0)
	v_pk_mul_f32 v[150:151], v[150:151], v[152:153]
	v_pk_mul_f32 v[84:85], v[148:149], v[84:85]
	v_pk_mul_f32 v[148:149], v[164:165], v[174:175]
	v_pk_mul_f32 v[126:127], v[162:163], v[126:127]
	v_pk_mul_f32 v[84:85], v[134:135], v[84:85]
	v_pk_mul_f32 v[150:151], v[136:137], v[150:151]
	v_pk_mul_f32 v[126:127], v[134:135], v[126:127]
	v_pk_mul_f32 v[148:149], v[136:137], v[148:149]
	v_pk_fma_f32 v[86:87], v[86:87], v[168:169], v[150:151]
	v_pk_fma_f32 v[102:103], v[102:103], v[166:167], v[84:85]
	v_pk_fma_f32 v[110:111], v[110:111], v[172:173], v[148:149]
	v_pk_fma_f32 v[118:119], v[118:119], v[170:171], v[126:127]
.LBB0_520:
	v_mov_b64_e32 v[84:85], s[22:23]
	v_cvt_pk_bf16_f32 v149, v86, v87
	v_add_u32_e32 v86, 0xa0, v146
	v_mad_i64_i32 v[84:85], s[2:3], v94, s77, v[84:85]
	v_ashrrev_i32_e32 v87, 31, v86
	v_lshl_add_u64 v[84:85], s[48:49], 1, v[84:85]
	v_cvt_pk_bf16_f32 v148, v102, v103
	v_pk_mul_f32 v[102:103], v[74:75], s[38:39] op_sel_hi:[1,0]
	v_lshlrev_b64 v[74:75], 6, v[86:87]
	v_lshl_add_u64 v[84:85], v[84:85], 0, v[132:133]
	v_cvt_pk_bf16_f32 v150, v118, v119
	v_cvt_pk_bf16_f32 v151, v110, v111
	v_pk_mul_f32 v[78:79], v[78:79], s[38:39] op_sel_hi:[1,0]
	v_pk_mul_f32 v[94:95], v[76:77], s[38:39] op_sel_hi:[1,0]
	v_pk_mul_f32 v[110:111], v[72:73], s[38:39] op_sel_hi:[1,0]
	s_and_b64 vcc, exec, s[6:7]
	v_lshl_add_u64 v[72:73], v[138:139], 0, v[74:75]
	v_lshl_add_u64 v[74:75], v[140:141], 0, v[74:75]
	s_cbranch_vccz .Lqst_6
	global_store_dwordx4 v[84:85], v[148:151], off
	s_branch .LBB0_522
.Lqst_6:
	v_mov_b64_e32 v[192:193], v[84:85]
	v_mov_b64_e32 v[194:195], v[148:149]
	v_mov_b64_e32 v[196:197], v[150:151]
	global_load_dwordx4 v[148:151], v[74:75], off
	global_load_dwordx4 v[162:165], v[74:75], off offset:16
	global_load_dwordx4 v[166:169], v[72:73], off
	global_load_dwordx4 v[170:173], v[72:73], off offset:16
	global_store_dwordx4 v[192:193], v[194:197], off
	v_and_b32_e32 v77, 64, v160
	v_xor_b32_e32 v76, 32, v160
	v_add_u32_e32 v77, 64, v77
	v_cmp_lt_i32_e32 vcc, v76, v77
	s_nop 1
	v_cndmask_b32_e32 v76, v160, v76, vcc
	v_lshlrev_b32_e32 v87, 2, v76
	ds_bpermute_b32 v76, v87, v94
	ds_bpermute_b32 v118, v87, v110
	ds_bpermute_b32 v77, v87, v95
	ds_bpermute_b32 v126, v87, v78
	ds_bpermute_b32 v127, v87, v79
	ds_bpermute_b32 v152, v87, v102
	ds_bpermute_b32 v153, v87, v103
	ds_bpermute_b32 v119, v87, v111
	s_waitcnt vmcnt(1) lgkmcnt(0)
	v_pk_mul_f32 v[126:127], v[150:151], v[126:127]
	v_pk_mul_f32 v[76:77], v[148:149], v[76:77]
	v_pk_mul_f32 v[148:149], v[164:165], v[152:153]
	v_pk_mul_f32 v[118:119], v[162:163], v[118:119]
	v_pk_mul_f32 v[76:77], v[134:135], v[76:77]
	v_pk_mul_f32 v[126:127], v[136:137], v[126:127]
	v_pk_mul_f32 v[118:119], v[134:135], v[118:119]
	v_pk_mul_f32 v[148:149], v[136:137], v[148:149]
	v_pk_fma_f32 v[78:79], v[78:79], v[168:169], v[126:127]
	v_pk_fma_f32 v[94:95], v[94:95], v[166:167], v[76:77]
	v_pk_fma_f32 v[102:103], v[102:103], v[172:173], v[148:149]
	v_pk_fma_f32 v[110:111], v[110:111], v[170:171], v[118:119]
.LBB0_522:
	v_mov_b64_e32 v[76:77], s[22:23]
	v_cvt_pk_bf16_f32 v149, v78, v79
	v_add_u32_e32 v78, 0xb0, v146
	v_mad_i64_i32 v[76:77], s[2:3], v86, s77, v[76:77]
	v_ashrrev_i32_e32 v79, 31, v78
	v_lshl_add_u64 v[76:77], s[48:49], 1, v[76:77]
	v_cvt_pk_bf16_f32 v148, v94, v95
	v_pk_mul_f32 v[94:95], v[66:67], s[38:39] op_sel_hi:[1,0]
	v_lshlrev_b64 v[66:67], 6, v[78:79]
	v_lshl_add_u64 v[76:77], v[76:77], 0, v[132:133]
	v_cvt_pk_bf16_f32 v150, v110, v111
	v_cvt_pk_bf16_f32 v151, v102, v103
	v_pk_mul_f32 v[70:71], v[70:71], s[38:39] op_sel_hi:[1,0]
	v_pk_mul_f32 v[86:87], v[68:69], s[38:39] op_sel_hi:[1,0]
	v_pk_mul_f32 v[102:103], v[64:65], s[38:39] op_sel_hi:[1,0]
	s_and_b64 vcc, exec, s[6:7]
	v_lshl_add_u64 v[64:65], v[138:139], 0, v[66:67]
	v_lshl_add_u64 v[66:67], v[140:141], 0, v[66:67]
	s_cbranch_vccz .Lqst_7
	global_store_dwordx4 v[76:77], v[148:151], off
	s_branch .LBB0_524
.Lqst_7:
	v_mov_b64_e32 v[192:193], v[76:77]
	v_mov_b64_e32 v[194:195], v[148:149]
	v_mov_b64_e32 v[196:197], v[150:151]
	global_load_dwordx4 v[146:149], v[66:67], off
	global_load_dwordx4 v[150:153], v[66:67], off offset:16
	global_load_dwordx4 v[162:165], v[64:65], off
	global_load_dwordx4 v[166:169], v[64:65], off offset:16
	global_store_dwordx4 v[192:193], v[194:197], off
	v_and_b32_e32 v69, 64, v160
	v_xor_b32_e32 v68, 32, v160
	v_add_u32_e32 v69, 64, v69
	v_cmp_lt_i32_e32 vcc, v68, v69
	s_nop 1
	v_cndmask_b32_e32 v68, v160, v68, vcc
	v_lshlrev_b32_e32 v79, 2, v68
	ds_bpermute_b32 v68, v79, v86
	ds_bpermute_b32 v110, v79, v102
	ds_bpermute_b32 v69, v79, v87
	ds_bpermute_b32 v118, v79, v70
	ds_bpermute_b32 v119, v79, v71
	ds_bpermute_b32 v126, v79, v94
	ds_bpermute_b32 v127, v79, v95
	ds_bpermute_b32 v111, v79, v103
	s_waitcnt vmcnt(1) lgkmcnt(0)
	v_pk_mul_f32 v[118:119], v[148:149], v[118:119]
	v_pk_mul_f32 v[68:69], v[146:147], v[68:69]
	v_pk_mul_f32 v[126:127], v[152:153], v[126:127]
	v_pk_mul_f32 v[110:111], v[150:151], v[110:111]
	v_pk_mul_f32 v[68:69], v[134:135], v[68:69]
	v_pk_mul_f32 v[118:119], v[136:137], v[118:119]
	v_pk_mul_f32 v[110:111], v[134:135], v[110:111]
	v_pk_mul_f32 v[126:127], v[136:137], v[126:127]
	v_pk_fma_f32 v[70:71], v[70:71], v[164:165], v[118:119]
	v_pk_fma_f32 v[86:87], v[86:87], v[162:163], v[68:69]
	v_pk_fma_f32 v[94:95], v[94:95], v[168:169], v[126:127]
	v_pk_fma_f32 v[102:103], v[102:103], v[166:167], v[110:111]
.LBB0_524:
	v_mov_b64_e32 v[68:69], s[22:23]
	v_mad_i64_i32 v[68:69], s[2:3], v78, s77, v[68:69]
	s_or_b32 s2, s48, 0x80
	s_mul_hi_i32 s3, s2, 0x2aaaaaab
	s_lshr_b32 s6, s3, 31
	s_lshr_b32 s3, s3, 4
	s_add_i32 s3, s3, s6
	s_mulk_i32 s3, 0x60
	s_sub_i32 s6, s2, s3
	v_lshl_add_u64 v[68:69], s[48:49], 1, v[68:69]
	s_cmp_eq_u32 s6, 64
	v_lshl_add_u64 v[68:69], v[68:69], 0, v[132:133]
	v_cvt_pk_bf16_f32 v146, v86, v87
	v_cvt_pk_bf16_f32 v147, v70, v71
	v_cvt_pk_bf16_f32 v148, v102, v103
	v_cvt_pk_bf16_f32 v149, v94, v95
	s_cselect_b64 s[2:3], -1, 0
	s_cmp_lg_u32 s6, 64
	v_pk_mul_f32 v[62:63], v[62:63], s[38:39] op_sel_hi:[1,0]
	v_pk_mul_f32 v[60:61], v[60:61], s[38:39] op_sel_hi:[1,0]
	v_pk_mul_f32 v[58:59], v[58:59], s[38:39] op_sel_hi:[1,0]
	v_pk_mul_f32 v[56:57], v[56:57], s[38:39] op_sel_hi:[1,0]
	s_cbranch_scc0 .Lqst_8
	global_store_dwordx4 v[68:69], v[146:149], off
	s_branch .LBB0_526
.Lqst_8:
	v_mov_b64_e32 v[192:193], v[68:69]
	v_mov_b64_e32 v[194:195], v[146:147]
	v_mov_b64_e32 v[196:197], v[148:149]
	global_load_dwordx4 v[146:149], v[122:123], off
	global_load_dwordx4 v[150:153], v[122:123], off offset:16
	global_load_dwordx4 v[162:165], v[120:121], off
	s_nop 0
	global_load_dwordx4 v[118:121], v[120:121], off offset:16
	global_store_dwordx4 v[192:193], v[194:197], off
	v_and_b32_e32 v71, 64, v160
	v_xor_b32_e32 v70, 32, v160
	v_add_u32_e32 v71, 64, v71
	v_cmp_lt_i32_e32 vcc, v70, v71
	s_nop 1
	v_cndmask_b32_e32 v70, v160, v70, vcc
	v_lshlrev_b32_e32 v79, 2, v70
	ds_bpermute_b32 v70, v79, v60
	ds_bpermute_b32 v78, v79, v56
	ds_bpermute_b32 v71, v79, v61
	ds_bpermute_b32 v86, v79, v62
	ds_bpermute_b32 v87, v79, v63
	ds_bpermute_b32 v94, v79, v58
	ds_bpermute_b32 v95, v79, v59
	ds_bpermute_b32 v79, v79, v57
	s_waitcnt vmcnt(1) lgkmcnt(0)
	v_pk_mul_f32 v[86:87], v[148:149], v[86:87]
	v_pk_mul_f32 v[70:71], v[146:147], v[70:71]
	v_pk_mul_f32 v[94:95], v[152:153], v[94:95]
	v_pk_mul_f32 v[78:79], v[150:151], v[78:79]
	v_pk_mul_f32 v[70:71], v[134:135], v[70:71]
	v_pk_mul_f32 v[86:87], v[136:137], v[86:87]
	v_pk_mul_f32 v[78:79], v[134:135], v[78:79]
	v_pk_mul_f32 v[94:95], v[136:137], v[94:95]
	v_pk_fma_f32 v[62:63], v[62:63], v[164:165], v[86:87]
	v_pk_fma_f32 v[60:61], v[60:61], v[162:163], v[70:71]
	v_pk_fma_f32 v[58:59], v[58:59], v[120:121], v[94:95]
	v_pk_fma_f32 v[56:57], v[56:57], v[118:119], v[78:79]
.LBB0_526:
	v_cvt_pk_bf16_f32 v60, v60, v61
	v_cvt_pk_bf16_f32 v61, v62, v63
	v_cvt_pk_bf16_f32 v62, v56, v57
	v_cndmask_b32_e64 v56, 0, 1, s[2:3]
	v_cvt_pk_bf16_f32 v63, v58, v59
	v_pk_mul_f32 v[54:55], v[54:55], s[38:39] op_sel_hi:[1,0]
	v_pk_mul_f32 v[52:53], v[52:53], s[38:39] op_sel_hi:[1,0]
	v_pk_mul_f32 v[50:51], v[50:51], s[38:39] op_sel_hi:[1,0]
	v_cmp_ne_u32_e64 s[6:7], 1, v56
	s_andn2_b64 vcc, exec, s[2:3]
	v_pk_mul_f32 v[48:49], v[48:49], s[38:39] op_sel_hi:[1,0]
	s_cbranch_vccz .Lqst_9
	global_store_dwordx4 v[124:125], v[60:63], off offset:256
	s_branch .LBB0_528
.Lqst_9:
	v_mov_b64_e32 v[192:193], v[124:125]
	v_mov_b64_e32 v[194:195], v[60:61]
	v_mov_b64_e32 v[196:197], v[62:63]
	global_load_dwordx4 v[56:59], v[114:115], off
	global_load_dwordx4 v[60:63], v[114:115], off offset:16
	global_load_dwordx4 v[118:121], v[112:113], off
	s_nop 0
	global_load_dwordx4 v[110:113], v[112:113], off offset:16
	global_store_dwordx4 v[192:193], v[194:197], off offset:256
	v_and_b32_e32 v71, 64, v160
	v_xor_b32_e32 v70, 32, v160
	v_add_u32_e32 v71, 64, v71
	v_cmp_lt_i32_e32 vcc, v70, v71
	s_nop 1
	v_cndmask_b32_e32 v70, v160, v70, vcc
	v_lshlrev_b32_e32 v79, 2, v70
	ds_bpermute_b32 v70, v79, v52
	ds_bpermute_b32 v78, v79, v48
	ds_bpermute_b32 v71, v79, v53
	ds_bpermute_b32 v86, v79, v54
	ds_bpermute_b32 v87, v79, v55
	ds_bpermute_b32 v94, v79, v50
	ds_bpermute_b32 v95, v79, v51
	ds_bpermute_b32 v79, v79, v49
	s_waitcnt vmcnt(1) lgkmcnt(0)
	v_pk_mul_f32 v[58:59], v[58:59], v[86:87]
	v_pk_mul_f32 v[56:57], v[56:57], v[70:71]
	v_pk_mul_f32 v[62:63], v[62:63], v[94:95]
	v_pk_mul_f32 v[60:61], v[60:61], v[78:79]
	v_pk_mul_f32 v[56:57], v[134:135], v[56:57]
	v_pk_mul_f32 v[58:59], v[136:137], v[58:59]
	v_pk_mul_f32 v[60:61], v[134:135], v[60:61]
	v_pk_mul_f32 v[62:63], v[136:137], v[62:63]
	v_pk_fma_f32 v[54:55], v[54:55], v[120:121], v[58:59]
	v_pk_fma_f32 v[52:53], v[52:53], v[118:119], v[56:57]
	v_pk_fma_f32 v[50:51], v[50:51], v[112:113], v[62:63]
	v_pk_fma_f32 v[48:49], v[48:49], v[110:111], v[60:61]
.LBB0_528:
	v_cvt_pk_bf16_f32 v52, v52, v53
	v_cvt_pk_bf16_f32 v53, v54, v55
	v_cvt_pk_bf16_f32 v54, v48, v49
	v_cvt_pk_bf16_f32 v55, v50, v51
	v_pk_mul_f32 v[46:47], v[46:47], s[38:39] op_sel_hi:[1,0]
	v_pk_mul_f32 v[44:45], v[44:45], s[38:39] op_sel_hi:[1,0]
	v_pk_mul_f32 v[42:43], v[42:43], s[38:39] op_sel_hi:[1,0]
	s_and_b64 vcc, exec, s[6:7]
	v_pk_mul_f32 v[40:41], v[40:41], s[38:39] op_sel_hi:[1,0]
	s_cbranch_vccz .Lqst_10
	global_store_dwordx4 v[116:117], v[52:55], off offset:256
	s_branch .LBB0_530
.Lqst_10:
	v_mov_b64_e32 v[192:193], v[116:117]
	v_mov_b64_e32 v[194:195], v[52:53]
	v_mov_b64_e32 v[196:197], v[54:55]
	global_load_dwordx4 v[48:51], v[106:107], off
	global_load_dwordx4 v[52:55], v[106:107], off offset:16
	global_load_dwordx4 v[56:59], v[104:105], off
	global_load_dwordx4 v[60:63], v[104:105], off offset:16
	global_store_dwordx4 v[192:193], v[194:197], off offset:256
	v_and_b32_e32 v71, 64, v160
	v_xor_b32_e32 v70, 32, v160
	v_add_u32_e32 v71, 64, v71
	v_cmp_lt_i32_e32 vcc, v70, v71
	s_nop 1
	v_cndmask_b32_e32 v70, v160, v70, vcc
	v_lshlrev_b32_e32 v79, 2, v70
	ds_bpermute_b32 v70, v79, v44
	ds_bpermute_b32 v78, v79, v40
	ds_bpermute_b32 v71, v79, v45
	ds_bpermute_b32 v86, v79, v46
	ds_bpermute_b32 v87, v79, v47
	ds_bpermute_b32 v94, v79, v42
	ds_bpermute_b32 v95, v79, v43
	ds_bpermute_b32 v79, v79, v41
	s_waitcnt vmcnt(1) lgkmcnt(0)
	v_pk_mul_f32 v[50:51], v[50:51], v[86:87]
	v_pk_mul_f32 v[48:49], v[48:49], v[70:71]
	v_pk_mul_f32 v[54:55], v[54:55], v[94:95]
	v_pk_mul_f32 v[52:53], v[52:53], v[78:79]
	v_pk_mul_f32 v[48:49], v[134:135], v[48:49]
	v_pk_mul_f32 v[50:51], v[136:137], v[50:51]
	v_pk_mul_f32 v[52:53], v[134:135], v[52:53]
	v_pk_mul_f32 v[54:55], v[136:137], v[54:55]
	v_pk_fma_f32 v[46:47], v[46:47], v[58:59], v[50:51]
	v_pk_fma_f32 v[44:45], v[44:45], v[56:57], v[48:49]
	v_pk_fma_f32 v[42:43], v[42:43], v[62:63], v[54:55]
	v_pk_fma_f32 v[40:41], v[40:41], v[60:61], v[52:53]
.LBB0_530:
	v_cvt_pk_bf16_f32 v44, v44, v45
	v_cvt_pk_bf16_f32 v45, v46, v47
	v_cvt_pk_bf16_f32 v46, v40, v41
	v_cvt_pk_bf16_f32 v47, v42, v43
	v_pk_mul_f32 v[38:39], v[38:39], s[38:39] op_sel_hi:[1,0]
	v_pk_mul_f32 v[36:37], v[36:37], s[38:39] op_sel_hi:[1,0]
	v_pk_mul_f32 v[34:35], v[34:35], s[38:39] op_sel_hi:[1,0]
	s_and_b64 vcc, exec, s[6:7]
	v_pk_mul_f32 v[32:33], v[32:33], s[38:39] op_sel_hi:[1,0]
	s_cbranch_vccz .Lqst_11
	global_store_dwordx4 v[108:109], v[44:47], off offset:256
	s_branch .LBB0_532
.Lqst_11:
	v_mov_b64_e32 v[192:193], v[108:109]
	v_mov_b64_e32 v[194:195], v[44:45]
	v_mov_b64_e32 v[196:197], v[46:47]
	global_load_dwordx4 v[40:43], v[98:99], off
	global_load_dwordx4 v[44:47], v[98:99], off offset:16
	global_load_dwordx4 v[48:51], v[96:97], off
	global_load_dwordx4 v[52:55], v[96:97], off offset:16
	global_store_dwordx4 v[192:193], v[194:197], off offset:256
	v_and_b32_e32 v57, 64, v160
	v_xor_b32_e32 v56, 32, v160
	v_add_u32_e32 v57, 64, v57
	v_cmp_lt_i32_e32 vcc, v56, v57
	s_nop 1
	v_cndmask_b32_e32 v56, v160, v56, vcc
	v_lshlrev_b32_e32 v59, 2, v56
	ds_bpermute_b32 v56, v59, v36
	ds_bpermute_b32 v58, v59, v32
	ds_bpermute_b32 v57, v59, v37
	ds_bpermute_b32 v60, v59, v38
	ds_bpermute_b32 v61, v59, v39
	ds_bpermute_b32 v62, v59, v34
	ds_bpermute_b32 v63, v59, v35
	ds_bpermute_b32 v59, v59, v33
	s_waitcnt vmcnt(1) lgkmcnt(0)
	v_pk_mul_f32 v[42:43], v[42:43], v[60:61]
	v_pk_mul_f32 v[40:41], v[40:41], v[56:57]
	v_pk_mul_f32 v[46:47], v[46:47], v[62:63]
	v_pk_mul_f32 v[44:45], v[44:45], v[58:59]
	v_pk_mul_f32 v[40:41], v[134:135], v[40:41]
	v_pk_mul_f32 v[42:43], v[136:137], v[42:43]
	v_pk_mul_f32 v[44:45], v[134:135], v[44:45]
	v_pk_mul_f32 v[46:47], v[136:137], v[46:47]
	v_pk_fma_f32 v[38:39], v[38:39], v[50:51], v[42:43]
	v_pk_fma_f32 v[36:37], v[36:37], v[48:49], v[40:41]
	v_pk_fma_f32 v[34:35], v[34:35], v[54:55], v[46:47]
	v_pk_fma_f32 v[32:33], v[32:33], v[52:53], v[44:45]
.LBB0_532:
	v_cvt_pk_bf16_f32 v36, v36, v37
	v_cvt_pk_bf16_f32 v37, v38, v39
	v_cvt_pk_bf16_f32 v38, v32, v33
	v_cvt_pk_bf16_f32 v39, v34, v35
	v_pk_mul_f32 v[30:31], v[30:31], s[38:39] op_sel_hi:[1,0]
	v_pk_mul_f32 v[28:29], v[28:29], s[38:39] op_sel_hi:[1,0]
	v_pk_mul_f32 v[26:27], v[26:27], s[38:39] op_sel_hi:[1,0]
	s_and_b64 vcc, exec, s[6:7]
	v_pk_mul_f32 v[24:25], v[24:25], s[38:39] op_sel_hi:[1,0]
	s_cbranch_vccz .Lqst_12
	global_store_dwordx4 v[100:101], v[36:39], off offset:256
	s_branch .LBB0_534
.Lqst_12:
	v_mov_b64_e32 v[192:193], v[100:101]
	v_mov_b64_e32 v[194:195], v[36:37]
	v_mov_b64_e32 v[196:197], v[38:39]
	global_load_dwordx4 v[32:35], v[90:91], off
	global_load_dwordx4 v[36:39], v[90:91], off offset:16
	global_load_dwordx4 v[40:43], v[88:89], off
	global_load_dwordx4 v[44:47], v[88:89], off offset:16
	global_store_dwordx4 v[192:193], v[194:197], off offset:256
	v_and_b32_e32 v49, 64, v160
	v_xor_b32_e32 v48, 32, v160
	v_add_u32_e32 v49, 64, v49
	v_cmp_lt_i32_e32 vcc, v48, v49
	s_nop 1
	v_cndmask_b32_e32 v48, v160, v48, vcc
	v_lshlrev_b32_e32 v51, 2, v48
	ds_bpermute_b32 v48, v51, v28
	ds_bpermute_b32 v50, v51, v24
	ds_bpermute_b32 v49, v51, v29
	ds_bpermute_b32 v52, v51, v30
	ds_bpermute_b32 v53, v51, v31
	ds_bpermute_b32 v54, v51, v26
	ds_bpermute_b32 v55, v51, v27
	ds_bpermute_b32 v51, v51, v25
	s_waitcnt vmcnt(1) lgkmcnt(0)
	v_pk_mul_f32 v[34:35], v[34:35], v[52:53]
	v_pk_mul_f32 v[32:33], v[32:33], v[48:49]
	v_pk_mul_f32 v[38:39], v[38:39], v[54:55]
	v_pk_mul_f32 v[36:37], v[36:37], v[50:51]
	v_pk_mul_f32 v[32:33], v[134:135], v[32:33]
	v_pk_mul_f32 v[34:35], v[136:137], v[34:35]
	v_pk_mul_f32 v[36:37], v[134:135], v[36:37]
	v_pk_mul_f32 v[38:39], v[136:137], v[38:39]
	v_pk_fma_f32 v[30:31], v[30:31], v[42:43], v[34:35]
	v_pk_fma_f32 v[28:29], v[28:29], v[40:41], v[32:33]
	v_pk_fma_f32 v[26:27], v[26:27], v[46:47], v[38:39]
	v_pk_fma_f32 v[24:25], v[24:25], v[44:45], v[36:37]
.LBB0_534:
	v_cvt_pk_bf16_f32 v28, v28, v29
	v_cvt_pk_bf16_f32 v29, v30, v31
	v_cvt_pk_bf16_f32 v30, v24, v25
	v_cvt_pk_bf16_f32 v31, v26, v27
	v_pk_mul_f32 v[22:23], v[22:23], s[38:39] op_sel_hi:[1,0]
	v_pk_mul_f32 v[20:21], v[20:21], s[38:39] op_sel_hi:[1,0]
	v_pk_mul_f32 v[18:19], v[18:19], s[38:39] op_sel_hi:[1,0]
	s_and_b64 vcc, exec, s[6:7]
	v_pk_mul_f32 v[16:17], v[16:17], s[38:39] op_sel_hi:[1,0]
	s_cbranch_vccz .Lqst_13
	global_store_dwordx4 v[92:93], v[28:31], off offset:256
	s_branch .LBB0_536
.Lqst_13:
	v_mov_b64_e32 v[192:193], v[92:93]
	v_mov_b64_e32 v[194:195], v[28:29]
	v_mov_b64_e32 v[196:197], v[30:31]
	global_load_dwordx4 v[24:27], v[82:83], off
	global_load_dwordx4 v[28:31], v[82:83], off offset:16
	global_load_dwordx4 v[32:35], v[80:81], off
	global_load_dwordx4 v[36:39], v[80:81], off offset:16
	global_store_dwordx4 v[192:193], v[194:197], off offset:256
	v_and_b32_e32 v41, 64, v160
	v_xor_b32_e32 v40, 32, v160
	v_add_u32_e32 v41, 64, v41
	v_cmp_lt_i32_e32 vcc, v40, v41
	s_nop 1
	v_cndmask_b32_e32 v40, v160, v40, vcc
	v_lshlrev_b32_e32 v43, 2, v40
	ds_bpermute_b32 v40, v43, v20
	ds_bpermute_b32 v42, v43, v16
	ds_bpermute_b32 v41, v43, v21
	ds_bpermute_b32 v44, v43, v22
	ds_bpermute_b32 v45, v43, v23
	ds_bpermute_b32 v46, v43, v18
	ds_bpermute_b32 v47, v43, v19
	ds_bpermute_b32 v43, v43, v17
	s_waitcnt vmcnt(1) lgkmcnt(0)
	v_pk_mul_f32 v[26:27], v[26:27], v[44:45]
	v_pk_mul_f32 v[24:25], v[24:25], v[40:41]
	v_pk_mul_f32 v[30:31], v[30:31], v[46:47]
	v_pk_mul_f32 v[28:29], v[28:29], v[42:43]
	v_pk_mul_f32 v[24:25], v[134:135], v[24:25]
	v_pk_mul_f32 v[26:27], v[136:137], v[26:27]
	v_pk_mul_f32 v[28:29], v[134:135], v[28:29]
	v_pk_mul_f32 v[30:31], v[136:137], v[30:31]
	v_pk_fma_f32 v[22:23], v[22:23], v[34:35], v[26:27]
	v_pk_fma_f32 v[20:21], v[20:21], v[32:33], v[24:25]
	v_pk_fma_f32 v[18:19], v[18:19], v[38:39], v[30:31]
	v_pk_fma_f32 v[16:17], v[16:17], v[36:37], v[28:29]
.LBB0_536:
	v_cvt_pk_bf16_f32 v20, v20, v21
	v_cvt_pk_bf16_f32 v21, v22, v23
	v_cvt_pk_bf16_f32 v22, v16, v17
	v_cvt_pk_bf16_f32 v23, v18, v19
	v_pk_mul_f32 v[14:15], v[14:15], s[38:39] op_sel_hi:[1,0]
	v_pk_mul_f32 v[12:13], v[12:13], s[38:39] op_sel_hi:[1,0]
	v_pk_mul_f32 v[10:11], v[10:11], s[38:39] op_sel_hi:[1,0]
	s_and_b64 vcc, exec, s[6:7]
	v_pk_mul_f32 v[8:9], v[8:9], s[38:39] op_sel_hi:[1,0]
	s_cbranch_vccz .Lqst_14
	global_store_dwordx4 v[84:85], v[20:23], off offset:256
	s_branch .LBB0_538
.Lqst_14:
	v_mov_b64_e32 v[192:193], v[84:85]
	v_mov_b64_e32 v[194:195], v[20:21]
	v_mov_b64_e32 v[196:197], v[22:23]
	global_load_dwordx4 v[16:19], v[74:75], off
	global_load_dwordx4 v[20:23], v[74:75], off offset:16
	global_load_dwordx4 v[24:27], v[72:73], off
	global_load_dwordx4 v[28:31], v[72:73], off offset:16
	global_store_dwordx4 v[192:193], v[194:197], off offset:256
	v_and_b32_e32 v33, 64, v160
	v_xor_b32_e32 v32, 32, v160
	v_add_u32_e32 v33, 64, v33
	v_cmp_lt_i32_e32 vcc, v32, v33
	s_nop 1
	v_cndmask_b32_e32 v32, v160, v32, vcc
	v_lshlrev_b32_e32 v35, 2, v32
	ds_bpermute_b32 v32, v35, v12
	ds_bpermute_b32 v34, v35, v8
	ds_bpermute_b32 v33, v35, v13
	ds_bpermute_b32 v36, v35, v14
	ds_bpermute_b32 v37, v35, v15
	ds_bpermute_b32 v38, v35, v10
	ds_bpermute_b32 v39, v35, v11
	ds_bpermute_b32 v35, v35, v9
	s_waitcnt vmcnt(1) lgkmcnt(0)
	v_pk_mul_f32 v[18:19], v[18:19], v[36:37]
	v_pk_mul_f32 v[16:17], v[16:17], v[32:33]
	v_pk_mul_f32 v[22:23], v[22:23], v[38:39]
	v_pk_mul_f32 v[20:21], v[20:21], v[34:35]
	v_pk_mul_f32 v[16:17], v[134:135], v[16:17]
	v_pk_mul_f32 v[18:19], v[136:137], v[18:19]
	v_pk_mul_f32 v[20:21], v[134:135], v[20:21]
	v_pk_mul_f32 v[22:23], v[136:137], v[22:23]
	v_pk_fma_f32 v[14:15], v[14:15], v[26:27], v[18:19]
	v_pk_fma_f32 v[12:13], v[12:13], v[24:25], v[16:17]
	v_pk_fma_f32 v[10:11], v[10:11], v[30:31], v[22:23]
	v_pk_fma_f32 v[8:9], v[8:9], v[28:29], v[20:21]
.LBB0_538:
	v_cvt_pk_bf16_f32 v12, v12, v13
	v_cvt_pk_bf16_f32 v13, v14, v15
	v_cvt_pk_bf16_f32 v14, v8, v9
	v_cvt_pk_bf16_f32 v15, v10, v11
	v_pk_mul_f32 v[6:7], v[6:7], s[38:39] op_sel_hi:[1,0]
	v_pk_mul_f32 v[4:5], v[4:5], s[38:39] op_sel_hi:[1,0]
	v_pk_mul_f32 v[2:3], v[2:3], s[38:39] op_sel_hi:[1,0]
	s_and_b64 vcc, exec, s[6:7]
	v_pk_mul_f32 v[0:1], v[0:1], s[38:39] op_sel_hi:[1,0]
	s_cbranch_vccz .Lqst_15
	global_store_dwordx4 v[76:77], v[12:15], off offset:256
	s_branch .LBB0_540
.Lqst_15:
	v_mov_b64_e32 v[192:193], v[76:77]
	v_mov_b64_e32 v[194:195], v[12:13]
	v_mov_b64_e32 v[196:197], v[14:15]
	global_load_dwordx4 v[8:11], v[66:67], off
	global_load_dwordx4 v[12:15], v[66:67], off offset:16
	global_load_dwordx4 v[16:19], v[64:65], off
	global_load_dwordx4 v[20:23], v[64:65], off offset:16
	global_store_dwordx4 v[192:193], v[194:197], off offset:256
	v_and_b32_e32 v25, 64, v160
	v_xor_b32_e32 v24, 32, v160
	v_add_u32_e32 v25, 64, v25
	v_cmp_lt_i32_e32 vcc, v24, v25
	s_nop 1
	v_cndmask_b32_e32 v24, v160, v24, vcc
	v_lshlrev_b32_e32 v27, 2, v24
	ds_bpermute_b32 v24, v27, v4
	ds_bpermute_b32 v26, v27, v0
	ds_bpermute_b32 v25, v27, v5
	ds_bpermute_b32 v28, v27, v6
	ds_bpermute_b32 v29, v27, v7
	ds_bpermute_b32 v30, v27, v2
	ds_bpermute_b32 v31, v27, v3
	ds_bpermute_b32 v27, v27, v1
	s_waitcnt vmcnt(1) lgkmcnt(0)
	v_pk_mul_f32 v[10:11], v[10:11], v[28:29]
	v_pk_mul_f32 v[8:9], v[8:9], v[24:25]
	v_pk_mul_f32 v[14:15], v[14:15], v[30:31]
	v_pk_mul_f32 v[12:13], v[12:13], v[26:27]
	v_pk_mul_f32 v[8:9], v[134:135], v[8:9]
	v_pk_mul_f32 v[10:11], v[136:137], v[10:11]
	v_pk_mul_f32 v[12:13], v[134:135], v[12:13]
	v_pk_mul_f32 v[14:15], v[136:137], v[14:15]
	v_pk_fma_f32 v[6:7], v[6:7], v[18:19], v[10:11]
	v_pk_fma_f32 v[4:5], v[4:5], v[16:17], v[8:9]
	v_pk_fma_f32 v[2:3], v[2:3], v[22:23], v[14:15]
	v_pk_fma_f32 v[0:1], v[0:1], v[20:21], v[12:13]
